# P0: conv_matrix gain loads hoisted (8 loads issued together, counted vmcnt) + cast_rows next-row prefetch
# baseline (speedup 1.0000x reference)
.LBB0_129:
	s_abs_i32 s3, s22
	s_mul_hi_u32 s20, s3, s34
	s_mul_i32 s21, s20, s29
	s_sub_i32 s3, s3, s21
	s_ashr_i32 s2, s22, 31
	s_add_i32 s21, s20, 1
	s_sub_i32 s22, s3, s29
	s_cmp_ge_u32 s3, s29
	s_cselect_b32 s20, s21, s20
	s_cselect_b32 s3, s22, s3
	s_add_i32 s21, s20, 1
	s_cmp_ge_u32 s3, s29
	s_cselect_b32 s3, s21, s20
	s_xor_b32 s3, s3, s2
	s_sub_i32 s45, s3, s2
	s_lshl_b32 s20, s45, 6
	v_or_b32_e32 v70, s20, v72
	v_cndmask_b32_e64 v66, 0, 1, s[16:17]
	v_cmp_ne_u32_e64 s[2:3], 1, v66
	s_andn2_b64 vcc, exec, s[16:17]
	v_ashrrev_i32_e32 v71, 31, v70
	s_cbranch_vccnz .LBB0_157
	v_lshl_add_u64 v[78:79], v[70:71], 2, s[12:13]
	global_load_dword v80, v[78:79], off
	global_load_dword v66, v[78:79], off offset:32
	global_load_dword v82, v[78:79], off offset:64
	global_load_dword v84, v[78:79], off offset:96
	global_load_dword v86, v[78:79], off offset:128
	global_load_dword v88, v[78:79], off offset:160
	global_load_dword v90, v[78:79], off offset:192
	global_load_dword v92, v[78:79], off offset:224
	s_waitcnt vmcnt(7)
	v_pk_mul_f32 v[78:79], v[18:19], v[80:81] op_sel_hi:[1,0]
	v_pk_mul_f32 v[80:81], v[20:21], v[80:81] op_sel_hi:[1,0]
	ds_write2_b32 v76, v78, v79 offset1:1
	ds_write2_b32 v76, v80, v81 offset0:2 offset1:3
	s_cbranch_execnz .LBB0_132

.LBB0_132:
	s_waitcnt vmcnt(6)
	v_pk_mul_f32 v[2:3], v[2:3], v[66:67] op_sel_hi:[1,0]
	v_add_u32_e32 v18, 0x420, v76
	ds_write2_b32 v18, v2, v3 offset1:1
	v_pk_mul_f32 v[2:3], v[4:5], v[66:67] op_sel_hi:[1,0]
	v_add_u32_e32 v4, 0x428, v76
	ds_write2_b32 v4, v2, v3 offset1:1
	s_and_b64 vcc, exec, s[2:3]
	v_add_u32_e32 v3, 0x840, v76
	v_add_u32_e32 v4, 0x848, v76
	s_cbranch_vccnz .LBB0_158
	s_waitcnt vmcnt(5)
	v_pk_mul_f32 v[18:19], v[22:23], v[82:83] op_sel_hi:[1,0]
	v_pk_mul_f32 v[20:21], v[24:25], v[82:83] op_sel_hi:[1,0]
	ds_write2_b32 v3, v18, v19 offset1:1
	ds_write2_b32 v4, v20, v21 offset1:1
	s_waitcnt vmcnt(4)
	v_mov_b32_e32 v2, v84
	s_cbranch_execnz .LBB0_135

.LBB0_135:
	s_waitcnt vmcnt(4)
	v_pk_mul_f32 v[4:5], v[6:7], v[2:3] op_sel_hi:[1,0]
	v_add_u32_e32 v3, 0xc60, v76
	ds_write2_b32 v3, v4, v5 offset1:1
	v_pk_mul_f32 v[2:3], v[8:9], v[2:3] op_sel_hi:[1,0]
	v_add_u32_e32 v4, 0xc68, v76
	ds_write2_b32 v4, v2, v3 offset1:1
	s_and_b64 vcc, exec, s[2:3]
	v_add_u32_e32 v3, 0x1080, v76
	v_add_u32_e32 v4, 0x1088, v76
	s_cbranch_vccnz .LBB0_159
	s_waitcnt vmcnt(3)
	v_pk_mul_f32 v[6:7], v[26:27], v[86:87] op_sel_hi:[1,0]
	v_pk_mul_f32 v[8:9], v[28:29], v[86:87] op_sel_hi:[1,0]
	ds_write2_b32 v3, v6, v7 offset1:1
	ds_write2_b32 v4, v8, v9 offset1:1
	s_waitcnt vmcnt(2)
	v_mov_b32_e32 v2, v88
	s_cbranch_execnz .LBB0_138

.LBB0_138:
	s_waitcnt vmcnt(2)
	v_pk_mul_f32 v[4:5], v[14:15], v[2:3] op_sel_hi:[1,0]
	v_add_u32_e32 v3, 0x14a0, v76
	ds_write2_b32 v3, v4, v5 offset1:1
	v_pk_mul_f32 v[2:3], v[16:17], v[2:3] op_sel_hi:[1,0]
	v_add_u32_e32 v4, 0x14a8, v76
	ds_write2_b32 v4, v2, v3 offset1:1
	s_and_b64 vcc, exec, s[2:3]
	v_add_u32_e32 v3, 0x18c0, v76
	v_add_u32_e32 v4, 0x18c8, v76
	s_cbranch_vccnz .LBB0_160
	s_waitcnt vmcnt(1)
	v_pk_mul_f32 v[6:7], v[30:31], v[90:91] op_sel_hi:[1,0]
	v_pk_mul_f32 v[8:9], v[32:33], v[90:91] op_sel_hi:[1,0]
	ds_write2_b32 v3, v6, v7 offset1:1
	ds_write2_b32 v4, v8, v9 offset1:1
	s_waitcnt vmcnt(0)
	v_mov_b32_e32 v2, v92
	s_cbranch_execnz .LBB0_141

.LBB0_321:
	s_add_i32 s92, 0, 0x24400
	s_mov_b32 s2, s92
	s_add_i32 s93, 0, 0x244d8
	s_waitcnt vmcnt(0)
	v_mov_b32_e32 v2, s2
	s_mov_b32 s2, s33
	ds_read2_b32 v[2:3], v2 offset1:1
	s_mov_b32 s2, s33
	s_cmpk_lt_i32 s64, 0x4000
	v_mov_b32_e32 v4, s2
	s_mov_b32 s2, s93
	ds_read2_b32 v[4:5], v4 offset1:1
	s_waitcnt lgkmcnt(1)
	v_readfirstlane_b32 s10, v2
	v_mov_b32_e32 v6, s2
	ds_read2_b32 v[6:7], v6 offset1:1
	v_readfirstlane_b32 s11, v3
	s_waitcnt lgkmcnt(1)
	v_readfirstlane_b32 s6, v4
	v_readfirstlane_b32 s7, v5
	v_mov_b32_e32 v2, 0
	s_waitcnt lgkmcnt(0)
	v_readfirstlane_b32 s8, v6
	v_readfirstlane_b32 s9, v7
	v_mov_b32_e32 v7, 0
	s_getreg_b32 s2, hwreg(HW_REG_HW_ID, 0, 6)
	s_cbranch_scc0 .LBB0_326
	v_mbcnt_lo_u32_b32 v2, -1, v2
	v_mbcnt_hi_u32_b32 v2, -1, v2
	s_lshl_b64 s[12:13], s[64:65], 6
	v_and_b32_e32 v8, 63, v2
	s_add_u32 s6, s6, s12
	v_lshlrev_b32_e32 v6, 2, v8
	s_addc_u32 s7, s7, s13
	v_lshl_add_u64 v[2:3], s[6:7], 0, v[6:7]
	s_mov_b64 s[6:7], 0x10380000
	s_ashr_i32 s89, s88, 31
	v_lshl_add_u64 v[2:3], v[2:3], 0, s[6:7]
	s_lshl_b64 s[6:7], s[88:89], 6
	s_lshl_b64 s[12:13], s[64:65], 11
	s_add_u32 s8, s8, s12
	v_lshlrev_b32_e32 v6, 3, v8
	s_addc_u32 s9, s9, s13
	v_lshl_add_u64 v[4:5], s[8:9], 0, v[6:7]
	s_mov_b64 s[8:9], 0x400
	v_lshl_add_u64 v[4:5], v[4:5], 0, s[8:9]
	s_lshl_b64 s[8:9], s[88:89], 11
	s_lshl_b64 s[12:13], s[64:65], 12
	s_add_u32 s10, s10, s12
	v_lshlrev_b32_e32 v6, 4, v8
	s_addc_u32 s11, s11, s13
	v_lshl_add_u64 v[6:7], s[10:11], 0, v[6:7]
	s_mov_b64 s[10:11], 0xc00
	v_cmp_gt_u32_e32 vcc, 16, v8
	v_cmp_eq_u32_e64 s[2:3], 0, v8
	v_lshl_add_u64 v[6:7], v[6:7], 0, s[10:11]
	s_lshl_b64 s[10:11], s[88:89], 12
	s_mov_b32 s14, s64
	global_load_dwordx4 v[100:103], v[6:7], off offset:-3072 nt
	global_load_dwordx4 v[104:107], v[6:7], off offset:-2048 nt
	global_load_dwordx4 v[108:111], v[6:7], off offset:-1024 nt
	global_load_dwordx4 v[112:115], v[6:7], off nt
	s_waitcnt vmcnt(0)
	s_branch .LBB0_324

.LBB0_324:
	s_waitcnt lgkmcnt(0)
	s_waitcnt vmcnt(4)
	v_mov_b64 v[8:9], v[100:101]
	v_mov_b64 v[10:11], v[102:103]
	v_mov_b64 v[12:13], v[104:105]
	v_mov_b64 v[14:15], v[106:107]
	v_mov_b64 v[16:17], v[108:109]
	v_mov_b64 v[18:19], v[110:111]
	v_mov_b64 v[20:21], v[112:113]
	v_mov_b64 v[22:23], v[114:115]
	s_add_i32 s12, s14, s88
	s_cmpk_lt_i32 s12, 0x4000
	s_cbranch_scc0 .Lcr_nopf
	v_lshl_add_u64 v[116:117], v[6:7], 0, s[10:11]
	global_load_dwordx4 v[100:103], v[116:117], off offset:-3072 nt
	global_load_dwordx4 v[104:107], v[116:117], off offset:-2048 nt
	global_load_dwordx4 v[108:111], v[116:117], off offset:-1024 nt
	global_load_dwordx4 v[112:115], v[116:117], off nt
.Lcr_nopf:
	v_mov_b32_e32 v24, 0
	v_mov_b32_e32 v25, 0
	v_mbcnt_lo_u32_b32 v24, -1, v24
	v_mbcnt_hi_u32_b32 v24, -1, v24
	v_lshlrev_b32_e32 v24, 2, v24
	v_xor_b32_e32 v24, 4, v24
	v_mov_b32_e32 v26, 0
	v_mbcnt_lo_u32_b32 v25, -1, v25
	v_mbcnt_hi_u32_b32 v25, -1, v25
	v_lshlrev_b32_e32 v25, 2, v25
	v_xor_b32_e32 v25, 8, v25
	v_mov_b32_e32 v27, 0
	v_mbcnt_lo_u32_b32 v26, -1, v26
	v_mbcnt_hi_u32_b32 v26, -1, v26
	v_lshlrev_b32_e32 v26, 2, v26
	v_xor_b32_e32 v26, 16, v26
	v_mov_b32_e32 v28, 0
	v_mbcnt_lo_u32_b32 v27, -1, v27
	v_mbcnt_hi_u32_b32 v27, -1, v27
	v_lshlrev_b32_e32 v27, 2, v27
	v_xor_b32_e32 v27, 32, v27
	v_mov_b32_e32 v29, 0
	v_mbcnt_lo_u32_b32 v28, -1, v28
	v_mbcnt_hi_u32_b32 v28, -1, v28
	v_lshlrev_b32_e32 v28, 2, v28
	v_xor_b32_e32 v28, 64, v28
	v_mul_f32_e32 v30, v9, v9
	v_mul_f32_e32 v31, v11, v11
	v_mul_f32_e32 v32, v13, v13
	v_mul_f32_e32 v33, v15, v15
	v_mul_f32_e32 v34, v17, v17
	v_mul_f32_e32 v35, v19, v19
	v_fmac_f32_e32 v30, v8, v8
	v_fmac_f32_e32 v31, v10, v10
	v_fmac_f32_e32 v32, v12, v12
	v_fmac_f32_e32 v33, v14, v14
	v_mul_f32_e32 v36, v21, v21
	v_mul_f32_e32 v37, v23, v23
	v_cvt_f16_f32_e32 v38, v8
	v_cvt_f16_f32_e32 v39, v10
	v_fmac_f32_e32 v34, v16, v16
	v_fmac_f32_e32 v35, v18, v18
	v_add_f32_e32 v8, v30, v31
	v_add_f32_e32 v10, v32, v33
	v_fmac_f32_e32 v36, v20, v20
	v_fmac_f32_e32 v37, v22, v22
	v_add_f32_e32 v30, v34, v35
	v_add_f32_e32 v8, v8, v10
	v_add_f32_e32 v31, v36, v37
	v_add_f32_e32 v8, v8, v30
	v_add_f32_e32 v8, v8, v31
	ds_bpermute_b32 v10, v24, v8
	v_cvt_f16_f32_e32 v12, v12
	v_cvt_f16_f32_sdwa v13, v13 dst_sel:WORD_1 dst_unused:UNUSED_PAD src0_sel:DWORD
	v_cvt_f16_f32_sdwa v9, v9 dst_sel:WORD_1 dst_unused:UNUSED_PAD src0_sel:DWORD
	v_cvt_f16_f32_sdwa v11, v11 dst_sel:WORD_1 dst_unused:UNUSED_PAD src0_sel:DWORD
	s_waitcnt lgkmcnt(0)
	v_add_f32_e32 v8, v8, v10
	ds_bpermute_b32 v10, v25, v8
	v_cvt_f16_f32_e32 v14, v14
	v_cvt_f16_f32_sdwa v15, v15 dst_sel:WORD_1 dst_unused:UNUSED_PAD src0_sel:DWORD
	v_mbcnt_lo_u32_b32 v29, -1, v29
	v_mbcnt_hi_u32_b32 v29, -1, v29
	s_waitcnt lgkmcnt(0)
	v_add_f32_e32 v8, v8, v10
	ds_bpermute_b32 v10, v26, v8
	v_lshlrev_b32_e32 v29, 2, v29
	v_xor_b32_e32 v29, 0x80, v29
	v_cvt_f16_f32_e32 v16, v16
	v_cvt_f16_f32_sdwa v17, v17 dst_sel:WORD_1 dst_unused:UNUSED_PAD src0_sel:DWORD
	s_waitcnt lgkmcnt(0)
	v_add_f32_e32 v24, v8, v10
	ds_bpermute_b32 v25, v27, v24
	v_or_b32_e32 v10, v13, v12
	v_or_b32_e32 v8, v9, v38
	v_or_b32_e32 v9, v11, v39
	v_or_b32_e32 v11, v15, v14
	s_waitcnt lgkmcnt(0)
	v_add_f32_e32 v13, v24, v25
	ds_bpermute_b32 v24, v28, v13
	global_store_dwordx2 v[4:5], v[8:9], off offset:-1024
	global_store_dwordx2 v[4:5], v[10:11], off offset:-512
	v_cvt_f16_f32_e32 v18, v18
	v_cvt_f16_f32_sdwa v19, v19 dst_sel:WORD_1 dst_unused:UNUSED_PAD src0_sel:DWORD
	v_cvt_f16_f32_e32 v20, v20
	s_waitcnt lgkmcnt(0)
	v_add_f32_e32 v8, v13, v24
	v_cvt_f16_f32_sdwa v21, v21 dst_sel:WORD_1 dst_unused:UNUSED_PAD src0_sel:DWORD
	v_cvt_f16_f32_e32 v22, v22
	v_cvt_f16_f32_sdwa v23, v23 dst_sel:WORD_1 dst_unused:UNUSED_PAD src0_sel:DWORD
	ds_bpermute_b32 v9, v29, v8
	v_or_b32_e32 v12, v17, v16
	v_or_b32_e32 v13, v19, v18
	v_or_b32_e32 v10, v21, v20
	v_or_b32_e32 v11, v23, v22
	global_store_dwordx2 v[4:5], v[12:13], off
	global_store_dwordx2 v[4:5], v[10:11], off offset:512
	s_and_saveexec_b64 s[12:13], vcc
	s_cbranch_execz .LBB0_323
	s_waitcnt lgkmcnt(0)
	v_add_f32_e32 v8, v8, v9
	v_cndmask_b32_e64 v8, 0, v8, s[2:3]
	global_store_dword v[2:3], v8, off
	s_branch .LBB0_323
